# P8 mainloop touches the tile's epilogue operands (x2, e) early so the epilogue loads hit cache
# speedup vs baseline: 1.0013x; 1.0013x over previous
; #define PG8_STAGE(bufoff, gbase, voff) do { _Pragma("unroll") for (int _i = 0; _i < 2; ++_i) \
;         __builtin_amdgcn_global_load_lds((const unsigned*)((const char*)(gbase) + (voff)[_i]), (PG8_LAS unsigned*)(lds + (bufoff) + ldsw + _i * 8192), 16, 0, 0); } while (0)
; #define PG8_LDA(dst, b, h) do { _Pragma("unroll") for (int m = 0; m < 4; ++m) _Pragma("unroll") for (int k = 0; k < 2; ++k) dst[m][k] = *(const PG8_LAS bf16x8*)(lds + PG8_SA(b, h) + aoff + m * 2048 + k * 1024); } while (0)
; #define PG8_LDB(dst, b, h) do { _Pragma("unroll") for (int n = 0; n < 2; ++n) _Pragma("unroll") for (int k = 0; k < 2; ++k) dst[n][k] = *(const PG8_LAS bf16x8*)(lds + PG8_SB(b, h) + boff + n * 2048 + k * 1024); } while (0)
; #define PG8_MMA(ai, bj, At, Bt) do { __builtin_amdgcn_s_setprio(1); _Pragma("unroll") for (int m = 0; m < 4; ++m) _Pragma("unroll") for (int n = 0; n < 2; ++n) _Pragma("unroll") for (int k = 0; k < 2; ++k) \
;         acc[ai][bj][m][n] = __builtin_amdgcn_mfma_f32_16x16x32_bf16(Bt[n][k], At[m][k], acc[ai][bj][m][n], 0, 0, 0); __builtin_amdgcn_s_setprio(0); } while (0)
; #define PG8_WAIT_V(n) asm volatile("s_waitcnt vmcnt(" #n ")" ::: "memory")
; #define PG8_WAIT_L(n) asm volatile("s_waitcnt lgkmcnt(" #n ")" ::: "memory")
; #define PG8_BAR __builtin_amdgcn_s_barrier()
; #define PG8_SCHED __builtin_amdgcn_sched_barrier(0)
; template <class Epi, class Sched, bool ALIGN_EPI = false, bool SP2 = false>
; __device__ __forceinline__ void gemm_phase(PG8_LAS unsigned char* lds, const Gemm g, const Sched& S, const Epi& E) {
;     ...
;             PG8_LDB(B0, 0, 0); PG8_LDB(B1, 0, 1); PG8_SCHED; PG8_LDA(At, 0, 0); PG8_STAGE(PG8_SA(1, 1), a1 + hstep, voffA);
;             PG8_WAIT_V(8); PG8_WAIT_L(0); PG8_BAR; PG8_MMA(0, 0, At, B0); PG8_MMA(0, 1, At, B1); PG8_BAR; PG8_SCHED;
;             PG8_LDA(At, 0, 1); PG8_STAGE(PG8_SB(0, 0), b2, voffB); PG8_STAGE(PG8_SB(0, 1), b2 + hstep, voffB); PG8_STAGE(PG8_SA(0, 0), a2, voffA);
.LBB0_1562:
	ds_read_b128 v[144:147], v155
	ds_read_b128 v[148:151], v155 offset:1024
	ds_read_b128 v[160:163], v155 offset:2048
	ds_read_b128 v[164:167], v155 offset:3072
	ds_read_b128 v[168:171], v156
	ds_read_b128 v[172:175], v156 offset:1024
	ds_read_b128 v[176:179], v156 offset:2048
	ds_read_b128 v[180:183], v156 offset:3072
	s_add_u32 s30, s28, 0xfff80080
	s_addc_u32 s31, s29, -1
	s_cmp_eq_u32 s53, 28
	s_cselect_b32 s35, s21, s31
	s_cselect_b32 s34, s49, s30
	s_cselect_b32 s31, s19, s52
	s_cselect_b32 s30, s50, s51
	v_lshl_add_u64 v[216:217], s[28:29], 0, v[136:137]
	s_add_i32 m0, s27, 0xc000
	ds_read_b128 v[184:187], v157
	ds_read_b128 v[188:191], v157 offset:1024
	ds_read_b128 v[192:195], v157 offset:2048
	ds_read_b128 v[196:199], v157 offset:3072
	ds_read_b128 v[200:203], v157 offset:4096
	ds_read_b128 v[204:207], v157 offset:5120
	ds_read_b128 v[208:211], v157 offset:6144
	ds_read_b128 v[212:215], v157 offset:7168
	global_load_lds_dwordx4 v[216:217], off
	v_lshl_add_u64 v[216:217], s[28:29], 0, v[138:139]
	s_add_i32 m0, s27, 0xe000
	s_nop 0
	global_load_lds_dwordx4 v[216:217], off
	s_waitcnt vmcnt(8)
	s_waitcnt lgkmcnt(0)
	s_barrier
	s_sub_i32 s86, s53, 6
	s_cmp_gt_u32 s86, 10
	s_cbranch_scc1 .Lp8_pf_done
	s_lshr_b32 s87, s39, 5
	v_mbcnt_lo_u32_b32 v247, -1, 0
	s_cmp_gt_u32 s86, 6
	v_mbcnt_hi_u32_b32 v247, -1, v247
	s_cbranch_scc1 .Lp8_pf_e
	s_lshl_b32 s86, s86, 2
	s_add_i32 s87, s87, s86
	s_lshl_b32 s86, s26, 8
	s_add_i32 s87, s87, s86
	s_lshl_b32 s87, s87, 13
	s_lshl_b32 s86, s48, 10
	s_add_i32 s87, s87, s86
	v_lshlrev_b32_e32 v247, 4, v247
	v_lshl_or_b32 v247, v247, 9, v247
	v_and_b32_e32 v247, 0xe380, v247
	v_add_u32_e32 v247, s87, v247
	global_load_dword v247, v247, s[4:5]
	s_branch .Lp8_pf_done
.Lp8_pf_e:
	s_sub_i32 s86, s86, 8
	s_lshl_b32 s86, s86, 3
	s_add_i32 s87, s87, s86
	s_lshl_b32 s86, s26, 8
	s_add_i32 s87, s87, s86
	s_lshl_b32 s87, s87, 12
	s_lshl_b32 s86, s48, 9
	s_add_i32 s87, s87, s86
	v_lshlrev_b32_e32 v247, 3, v247
	v_lshl_or_b32 v247, v247, 9, v247
	v_and_b32_e32 v247, 0xf180, v247
	v_add_u32_e32 v247, s87, v247
	global_load_dword v247, v247, s[10:11]
.Lp8_pf_done:
	s_setprio 1
	s_waitcnt lgkmcnt(0)
	v_mfma_f32_16x16x32_bf16 v[124:127], v[144:147], v[184:187], v[124:127]
	v_mfma_f32_16x16x32_bf16 v[120:123], v[160:163], v[184:187], v[120:123]
	v_mfma_f32_16x16x32_bf16 v[108:111], v[144:147], v[192:195], v[108:111]
	v_mfma_f32_16x16x32_bf16 v[104:107], v[160:163], v[192:195], v[104:107]
	v_mfma_f32_16x16x32_bf16 v[92:95], v[144:147], v[200:203], v[92:95]
	v_mfma_f32_16x16x32_bf16 v[88:91], v[160:163], v[200:203], v[88:91]
	v_mfma_f32_16x16x32_bf16 v[76:79], v[144:147], v[208:211], v[76:79]
	v_mfma_f32_16x16x32_bf16 v[72:75], v[160:163], v[208:211], v[72:75]
	v_mfma_f32_16x16x32_bf16 v[124:127], v[148:151], v[188:191], v[124:127]
	v_mfma_f32_16x16x32_bf16 v[120:123], v[164:167], v[188:191], v[120:123]
	v_mfma_f32_16x16x32_bf16 v[108:111], v[148:151], v[196:199], v[108:111]
	v_mfma_f32_16x16x32_bf16 v[104:107], v[164:167], v[196:199], v[104:107]
	v_mfma_f32_16x16x32_bf16 v[92:95], v[148:151], v[204:207], v[92:95]
	v_mfma_f32_16x16x32_bf16 v[88:91], v[164:167], v[204:207], v[88:91]
	v_mfma_f32_16x16x32_bf16 v[76:79], v[148:151], v[212:215], v[76:79]
	v_mfma_f32_16x16x32_bf16 v[72:75], v[164:167], v[212:215], v[72:75]
	s_setprio 0
	s_setprio 1
	v_mfma_f32_16x16x32_bf16 v[116:119], v[168:171], v[184:187], v[116:119]
	v_mfma_f32_16x16x32_bf16 v[112:115], v[176:179], v[184:187], v[112:115]
	v_mfma_f32_16x16x32_bf16 v[100:103], v[168:171], v[192:195], v[100:103]
	v_mfma_f32_16x16x32_bf16 v[96:99], v[176:179], v[192:195], v[96:99]
	v_mfma_f32_16x16x32_bf16 v[84:87], v[168:171], v[200:203], v[84:87]
	v_mfma_f32_16x16x32_bf16 v[80:83], v[176:179], v[200:203], v[80:83]
	v_mfma_f32_16x16x32_bf16 v[68:71], v[168:171], v[208:211], v[68:71]
	v_mfma_f32_16x16x32_bf16 v[64:67], v[176:179], v[208:211], v[64:67]
	v_mfma_f32_16x16x32_bf16 v[116:119], v[172:175], v[188:191], v[116:119]
	v_mfma_f32_16x16x32_bf16 v[112:115], v[180:183], v[188:191], v[112:115]
	v_mfma_f32_16x16x32_bf16 v[100:103], v[172:175], v[196:199], v[100:103]
	v_mfma_f32_16x16x32_bf16 v[96:99], v[180:183], v[196:199], v[96:99]
	v_mfma_f32_16x16x32_bf16 v[84:87], v[172:175], v[204:207], v[84:87]
	v_mfma_f32_16x16x32_bf16 v[80:83], v[180:183], v[204:207], v[80:83]
	v_mfma_f32_16x16x32_bf16 v[68:71], v[172:175], v[212:215], v[68:71]
	v_mfma_f32_16x16x32_bf16 v[64:67], v[180:183], v[212:215], v[64:67]
	s_setprio 0
	s_barrier
	s_add_i32 s55, s46, s39
	v_lshl_add_u64 v[216:217], s[30:31], 0, v[130:131]
	s_mov_b32 m0, s55
	ds_read_b128 v[184:187], v157 offset:16384
	ds_read_b128 v[188:191], v157 offset:17408
	ds_read_b128 v[192:195], v157 offset:18432
	ds_read_b128 v[196:199], v157 offset:19456
	ds_read_b128 v[200:203], v157 offset:20480
	ds_read_b128 v[204:207], v157 offset:21504
	ds_read_b128 v[208:211], v157 offset:22528
	ds_read_b128 v[212:215], v157 offset:23552
	global_load_lds_dwordx4 v[216:217], off
	s_add_i32 m0, s55, 0x2000
	s_add_u32 s56, s30, 0x80000
	v_lshl_add_u64 v[218:219], s[30:31], 0, v[134:135]
	s_addc_u32 s57, s31, 0
	s_add_i32 s55, s47, s39
	global_load_lds_dwordx4 v[218:219], off
	v_lshl_add_u64 v[220:221], s[56:57], 0, v[130:131]
	s_mov_b32 m0, s55
	v_lshl_add_u64 v[222:223], s[34:35], 0, v[132:133]
	global_load_lds_dwordx4 v[220:221], off
	v_lshl_add_u64 v[220:221], s[56:57], 0, v[134:135]
	s_add_i32 m0, s55, 0x2000
	s_nop 0
	global_load_lds_dwordx4 v[220:221], off
	v_lshl_add_u64 v[220:221], s[34:35], 0, v[128:129]
	s_mov_b32 m0, s27
	s_nop 0
	global_load_lds_dwordx4 v[220:221], off
	s_mov_b32 m0, s40
	s_nop 0
	global_load_lds_dwordx4 v[222:223], off
	s_waitcnt vmcnt(8)
	s_waitcnt lgkmcnt(0)
	s_barrier
; #define PG8_STAGE(bufoff, gbase, voff) do { _Pragma("unroll") for (int _i = 0; _i < 2; ++_i) \
;         __builtin_amdgcn_global_load_lds((const unsigned*)((const char*)(gbase) + (voff)[_i]), (PG8_LAS unsigned*)(lds + (bufoff) + ldsw + _i * 8192), 16, 0, 0); } while (0)
; #define PG8_LDA(dst, b, h) do { _Pragma("unroll") for (int m = 0; m < 4; ++m) _Pragma("unroll") for (int k = 0; k < 2; ++k) dst[m][k] = *(const PG8_LAS bf16x8*)(lds + PG8_SA(b, h) + aoff + m * 2048 + k * 1024); } while (0)
; #define PG8_LDB(dst, b, h) do { _Pragma("unroll") for (int n = 0; n < 2; ++n) _Pragma("unroll") for (int k = 0; k < 2; ++k) dst[n][k] = *(const PG8_LAS bf16x8*)(lds + PG8_SB(b, h) + boff + n * 2048 + k * 1024); } while (0)
; #define PG8_MMA(ai, bj, At, Bt) do { __builtin_amdgcn_s_setprio(1); _Pragma("unroll") for (int m = 0; m < 4; ++m) _Pragma("unroll") for (int n = 0; n < 2; ++n) _Pragma("unroll") for (int k = 0; k < 2; ++k) \
;         acc[ai][bj][m][n] = __builtin_amdgcn_mfma_f32_16x16x32_bf16(Bt[n][k], At[m][k], acc[ai][bj][m][n], 0, 0, 0); __builtin_amdgcn_s_setprio(0); } while (0)
; #define PG8_WAIT_V(n) asm volatile("s_waitcnt vmcnt(" #n ")" ::: "memory")
; #define PG8_WAIT_L(n) asm volatile("s_waitcnt lgkmcnt(" #n ")" ::: "memory")
; #define PG8_BAR __builtin_amdgcn_s_barrier()
; #define PG8_SCHED __builtin_amdgcn_sched_barrier(0)
; template <class Epi, class Sched, bool ALIGN_EPI = false, bool SP2 = false>
; __device__ __forceinline__ void gemm_phase(PG8_LAS unsigned char* lds, const Gemm g, const Sched& S, const Epi& E) {
;     ...
;             PG8_WAIT_V(8); PG8_WAIT_L(0); PG8_BAR; PG8_MMA(1, 0, At, B0); PG8_MMA(1, 1, At, B1); PG8_BAR; PG8_SCHED;
;             PG8_LDB(B0, 1, 0); PG8_LDB(B1, 1, 1); PG8_SCHED; PG8_LDA(At, 1, 0); PG8_STAGE(PG8_SA(0, 1), a2 + hstep, voffA);
;             PG8_WAIT_V(8); PG8_WAIT_L(0); PG8_BAR; PG8_MMA(0, 0, At, B0); PG8_MMA(0, 1, At, B1); PG8_BAR; PG8_SCHED;
	s_setprio 1
	s_waitcnt lgkmcnt(0)
	v_mfma_f32_16x16x32_bf16 v[60:63], v[144:147], v[184:187], v[60:63]
	v_mfma_f32_16x16x32_bf16 v[56:59], v[160:163], v[184:187], v[56:59]
	v_mfma_f32_16x16x32_bf16 v[44:47], v[144:147], v[192:195], v[44:47]
	v_mfma_f32_16x16x32_bf16 v[40:43], v[160:163], v[192:195], v[40:43]
	v_mfma_f32_16x16x32_bf16 v[28:31], v[144:147], v[200:203], v[28:31]
	v_mfma_f32_16x16x32_bf16 v[24:27], v[160:163], v[200:203], v[24:27]
	v_mfma_f32_16x16x32_bf16 v[12:15], v[144:147], v[208:211], v[12:15]
	v_mfma_f32_16x16x32_bf16 v[8:11], v[160:163], v[208:211], v[8:11]
	v_mfma_f32_16x16x32_bf16 v[60:63], v[148:151], v[188:191], v[60:63]
	v_mfma_f32_16x16x32_bf16 v[56:59], v[164:167], v[188:191], v[56:59]
	v_mfma_f32_16x16x32_bf16 v[44:47], v[148:151], v[196:199], v[44:47]
	v_mfma_f32_16x16x32_bf16 v[40:43], v[164:167], v[196:199], v[40:43]
	v_mfma_f32_16x16x32_bf16 v[28:31], v[148:151], v[204:207], v[28:31]
	v_mfma_f32_16x16x32_bf16 v[24:27], v[164:167], v[204:207], v[24:27]
	v_mfma_f32_16x16x32_bf16 v[12:15], v[148:151], v[212:215], v[12:15]
	v_mfma_f32_16x16x32_bf16 v[8:11], v[164:167], v[212:215], v[8:11]
	s_setprio 0
	s_setprio 1
	v_mfma_f32_16x16x32_bf16 v[52:55], v[168:171], v[184:187], v[52:55]
	v_mfma_f32_16x16x32_bf16 v[48:51], v[176:179], v[184:187], v[48:51]
	v_mfma_f32_16x16x32_bf16 v[36:39], v[168:171], v[192:195], v[36:39]
	v_mfma_f32_16x16x32_bf16 v[32:35], v[176:179], v[192:195], v[32:35]
	v_mfma_f32_16x16x32_bf16 v[20:23], v[168:171], v[200:203], v[20:23]
	v_mfma_f32_16x16x32_bf16 v[16:19], v[176:179], v[200:203], v[16:19]
	v_mfma_f32_16x16x32_bf16 v[4:7], v[168:171], v[208:211], v[4:7]
	v_mfma_f32_16x16x32_bf16 v[0:3], v[176:179], v[208:211], v[0:3]
	v_mfma_f32_16x16x32_bf16 v[52:55], v[172:175], v[188:191], v[52:55]
	v_mfma_f32_16x16x32_bf16 v[48:51], v[180:183], v[188:191], v[48:51]
	v_mfma_f32_16x16x32_bf16 v[36:39], v[172:175], v[196:199], v[36:39]
	v_mfma_f32_16x16x32_bf16 v[32:35], v[180:183], v[196:199], v[32:35]
	v_mfma_f32_16x16x32_bf16 v[20:23], v[172:175], v[204:207], v[20:23]
	v_mfma_f32_16x16x32_bf16 v[16:19], v[180:183], v[204:207], v[16:19]
	v_mfma_f32_16x16x32_bf16 v[4:7], v[172:175], v[212:215], v[4:7]
	v_mfma_f32_16x16x32_bf16 v[0:3], v[180:183], v[212:215], v[0:3]
	s_setprio 0
	s_barrier
	s_add_i32 s55, 0, 0x18000
	v_add_u32_e32 v159, s55, v153
	s_add_i32 s56, 0, 0x1c000
	ds_read_b128 v[144:147], v159
	ds_read_b128 v[148:151], v159 offset:1024
	ds_read_b128 v[160:163], v159 offset:2048
	ds_read_b128 v[164:167], v159 offset:3072
	v_add_u32_e32 v159, s56, v153
	ds_read_b128 v[168:171], v159
	ds_read_b128 v[172:175], v159 offset:1024
	ds_read_b128 v[176:179], v159 offset:2048
	ds_read_b128 v[180:183], v159 offset:3072
	s_add_u32 s34, s34, 0x80000
	s_addc_u32 s35, s35, 0
	s_mov_b32 m0, s41
	v_lshl_add_u64 v[224:225], s[34:35], 0, v[128:129]
	ds_read_b128 v[184:187], v157 offset:32768
	ds_read_b128 v[188:191], v157 offset:33792
	ds_read_b128 v[192:195], v157 offset:34816
	ds_read_b128 v[196:199], v157 offset:35840
	ds_read_b128 v[200:203], v157 offset:36864
	ds_read_b128 v[204:207], v157 offset:37888
	ds_read_b128 v[208:211], v157 offset:38912
	ds_read_b128 v[212:215], v157 offset:39936
	global_load_lds_dwordx4 v[224:225], off
	v_lshl_add_u64 v[224:225], s[34:35], 0, v[132:133]
	s_mov_b32 m0, s42
	s_nop 0
	global_load_lds_dwordx4 v[224:225], off
	s_waitcnt vmcnt(8)
	s_waitcnt lgkmcnt(0)
	s_barrier
	s_setprio 1
	s_waitcnt lgkmcnt(0)
	v_mfma_f32_16x16x32_bf16 v[124:127], v[144:147], v[184:187], v[124:127]
	v_mfma_f32_16x16x32_bf16 v[120:123], v[160:163], v[184:187], v[120:123]
	v_mfma_f32_16x16x32_bf16 v[108:111], v[144:147], v[192:195], v[108:111]
	v_mfma_f32_16x16x32_bf16 v[104:107], v[160:163], v[192:195], v[104:107]
	v_mfma_f32_16x16x32_bf16 v[92:95], v[144:147], v[200:203], v[92:95]
	v_mfma_f32_16x16x32_bf16 v[88:91], v[160:163], v[200:203], v[88:91]
	v_mfma_f32_16x16x32_bf16 v[76:79], v[144:147], v[208:211], v[76:79]
	v_mfma_f32_16x16x32_bf16 v[72:75], v[160:163], v[208:211], v[72:75]
	v_mfma_f32_16x16x32_bf16 v[124:127], v[148:151], v[188:191], v[124:127]
	v_mfma_f32_16x16x32_bf16 v[120:123], v[164:167], v[188:191], v[120:123]
	v_mfma_f32_16x16x32_bf16 v[108:111], v[148:151], v[196:199], v[108:111]
	v_mfma_f32_16x16x32_bf16 v[104:107], v[164:167], v[196:199], v[104:107]
	v_mfma_f32_16x16x32_bf16 v[92:95], v[148:151], v[204:207], v[92:95]
	v_mfma_f32_16x16x32_bf16 v[88:91], v[164:167], v[204:207], v[88:91]
	v_mfma_f32_16x16x32_bf16 v[76:79], v[148:151], v[212:215], v[76:79]
	v_mfma_f32_16x16x32_bf16 v[72:75], v[164:167], v[212:215], v[72:75]
	s_setprio 0
	s_setprio 1
	v_mfma_f32_16x16x32_bf16 v[116:119], v[168:171], v[184:187], v[116:119]
	v_mfma_f32_16x16x32_bf16 v[112:115], v[176:179], v[184:187], v[112:115]
	v_mfma_f32_16x16x32_bf16 v[100:103], v[168:171], v[192:195], v[100:103]
	v_mfma_f32_16x16x32_bf16 v[96:99], v[176:179], v[192:195], v[96:99]
	v_mfma_f32_16x16x32_bf16 v[84:87], v[168:171], v[200:203], v[84:87]
	v_mfma_f32_16x16x32_bf16 v[80:83], v[176:179], v[200:203], v[80:83]
	v_mfma_f32_16x16x32_bf16 v[68:71], v[168:171], v[208:211], v[68:71]
	v_mfma_f32_16x16x32_bf16 v[64:67], v[176:179], v[208:211], v[64:67]
	v_mfma_f32_16x16x32_bf16 v[116:119], v[172:175], v[188:191], v[116:119]
	v_mfma_f32_16x16x32_bf16 v[112:115], v[180:183], v[188:191], v[112:115]
	v_mfma_f32_16x16x32_bf16 v[100:103], v[172:175], v[196:199], v[100:103]
	v_mfma_f32_16x16x32_bf16 v[96:99], v[180:183], v[196:199], v[96:99]
	v_mfma_f32_16x16x32_bf16 v[84:87], v[172:175], v[204:207], v[84:87]
	v_mfma_f32_16x16x32_bf16 v[80:83], v[180:183], v[204:207], v[80:83]
	v_mfma_f32_16x16x32_bf16 v[68:71], v[172:175], v[212:215], v[68:71]
	v_mfma_f32_16x16x32_bf16 v[64:67], v[180:183], v[212:215], v[64:67]
	s_setprio 0
	s_barrier
; #define PG8_STAGE(bufoff, gbase, voff) do { _Pragma("unroll") for (int _i = 0; _i < 2; ++_i) \
;         __builtin_amdgcn_global_load_lds((const unsigned*)((const char*)(gbase) + (voff)[_i]), (PG8_LAS unsigned*)(lds + (bufoff) + ldsw + _i * 8192), 16, 0, 0); } while (0)
; #define PG8_LDA(dst, b, h) do { _Pragma("unroll") for (int m = 0; m < 4; ++m) _Pragma("unroll") for (int k = 0; k < 2; ++k) dst[m][k] = *(const PG8_LAS bf16x8*)(lds + PG8_SA(b, h) + aoff + m * 2048 + k * 1024); } while (0)
; #define PG8_MMA(ai, bj, At, Bt) do { __builtin_amdgcn_s_setprio(1); _Pragma("unroll") for (int m = 0; m < 4; ++m) _Pragma("unroll") for (int n = 0; n < 2; ++n) _Pragma("unroll") for (int k = 0; k < 2; ++k) \
;         acc[ai][bj][m][n] = __builtin_amdgcn_mfma_f32_16x16x32_bf16(Bt[n][k], At[m][k], acc[ai][bj][m][n], 0, 0, 0); __builtin_amdgcn_s_setprio(0); } while (0)
; #define PG8_WAIT_V(n) asm volatile("s_waitcnt vmcnt(" #n ")" ::: "memory")
; #define PG8_WAIT_L(n) asm volatile("s_waitcnt lgkmcnt(" #n ")" ::: "memory")
; #define PG8_BAR __builtin_amdgcn_s_barrier()
; #define PG8_SCHED __builtin_amdgcn_sched_barrier(0)
; template <class Epi, class Sched, bool ALIGN_EPI = false, bool SP2 = false>
; __device__ __forceinline__ void gemm_phase(PG8_LAS unsigned char* lds, const Gemm g, const Sched& S, const Epi& E) {
;     ...
;         for (int t = 0; t < nt; t += 2) {
;     ...
;             PG8_LDA(At, 1, 1); PG8_STAGE(PG8_SB(1, 0), b3, voffB); PG8_STAGE(PG8_SB(1, 1), b3 + hstep, voffB); PG8_STAGE(PG8_SA(1, 0), a3, voffA);
;             PG8_WAIT_V(8); PG8_WAIT_L(0); PG8_BAR; PG8_MMA(1, 0, At, B0); PG8_MMA(1, 1, At, B1); PG8_BAR; PG8_SCHED;
	s_add_i32 s34, s55, s39
	v_lshl_add_u64 v[216:217], v[216:217], 0, s[14:15]
	s_mov_b32 m0, s34
	ds_read_b128 v[184:187], v157 offset:49152
	ds_read_b128 v[188:191], v157 offset:50176
	ds_read_b128 v[192:195], v157 offset:51200
	ds_read_b128 v[196:199], v157 offset:52224
	ds_read_b128 v[200:203], v157 offset:53248
	ds_read_b128 v[204:207], v157 offset:54272
	ds_read_b128 v[208:211], v157 offset:55296
	ds_read_b128 v[212:215], v157 offset:56320
	global_load_lds_dwordx4 v[216:217], off
	s_add_i32 m0, s34, 0x2000
	s_add_u32 s30, s30, 0x80080
	v_lshl_add_u64 v[216:217], v[218:219], 0, s[14:15]
	s_addc_u32 s31, s31, 0
	s_add_i32 s34, s56, s39
	global_load_lds_dwordx4 v[216:217], off
	v_lshl_add_u64 v[216:217], s[30:31], 0, v[130:131]
	s_mov_b32 m0, s34
	s_nop 0
	global_load_lds_dwordx4 v[216:217], off
	v_lshl_add_u64 v[216:217], s[30:31], 0, v[134:135]
	s_add_i32 m0, s34, 0x2000
	s_nop 0
	global_load_lds_dwordx4 v[216:217], off
	v_lshl_add_u64 v[216:217], v[220:221], 0, s[14:15]
	s_mov_b32 m0, s44
	s_nop 0
	global_load_lds_dwordx4 v[216:217], off
	v_lshl_add_u64 v[216:217], v[222:223], 0, s[14:15]
	s_mov_b32 m0, s45
	s_nop 0
	global_load_lds_dwordx4 v[216:217], off
	s_waitcnt vmcnt(8)
	s_waitcnt lgkmcnt(0)
	s_barrier
	s_setprio 1
	s_waitcnt lgkmcnt(0)
	v_mfma_f32_16x16x32_bf16 v[60:63], v[144:147], v[184:187], v[60:63]
	v_mfma_f32_16x16x32_bf16 v[56:59], v[160:163], v[184:187], v[56:59]
	v_mfma_f32_16x16x32_bf16 v[44:47], v[144:147], v[192:195], v[44:47]
	v_mfma_f32_16x16x32_bf16 v[40:43], v[160:163], v[192:195], v[40:43]
	v_mfma_f32_16x16x32_bf16 v[28:31], v[144:147], v[200:203], v[28:31]
	v_mfma_f32_16x16x32_bf16 v[24:27], v[160:163], v[200:203], v[24:27]
	v_mfma_f32_16x16x32_bf16 v[12:15], v[144:147], v[208:211], v[12:15]
	v_mfma_f32_16x16x32_bf16 v[8:11], v[160:163], v[208:211], v[8:11]
	v_mfma_f32_16x16x32_bf16 v[60:63], v[148:151], v[188:191], v[60:63]
	v_mfma_f32_16x16x32_bf16 v[56:59], v[164:167], v[188:191], v[56:59]
	v_mfma_f32_16x16x32_bf16 v[44:47], v[148:151], v[196:199], v[44:47]
	v_mfma_f32_16x16x32_bf16 v[40:43], v[164:167], v[196:199], v[40:43]
	v_mfma_f32_16x16x32_bf16 v[28:31], v[148:151], v[204:207], v[28:31]
	v_mfma_f32_16x16x32_bf16 v[24:27], v[164:167], v[204:207], v[24:27]
	v_mfma_f32_16x16x32_bf16 v[12:15], v[148:151], v[212:215], v[12:15]
	v_mfma_f32_16x16x32_bf16 v[8:11], v[164:167], v[212:215], v[8:11]
	s_setprio 0
	s_setprio 1
	v_mfma_f32_16x16x32_bf16 v[52:55], v[168:171], v[184:187], v[52:55]
	v_mfma_f32_16x16x32_bf16 v[48:51], v[176:179], v[184:187], v[48:51]
	v_mfma_f32_16x16x32_bf16 v[36:39], v[168:171], v[192:195], v[36:39]
	v_mfma_f32_16x16x32_bf16 v[32:35], v[176:179], v[192:195], v[32:35]
	v_mfma_f32_16x16x32_bf16 v[20:23], v[168:171], v[200:203], v[20:23]
	v_mfma_f32_16x16x32_bf16 v[16:19], v[176:179], v[200:203], v[16:19]
	v_mfma_f32_16x16x32_bf16 v[4:7], v[168:171], v[208:211], v[4:7]
	v_mfma_f32_16x16x32_bf16 v[0:3], v[176:179], v[208:211], v[0:3]
	v_mfma_f32_16x16x32_bf16 v[52:55], v[172:175], v[188:191], v[52:55]
	v_mfma_f32_16x16x32_bf16 v[48:51], v[180:183], v[188:191], v[48:51]
	v_mfma_f32_16x16x32_bf16 v[36:39], v[172:175], v[196:199], v[36:39]
	v_mfma_f32_16x16x32_bf16 v[32:35], v[180:183], v[196:199], v[32:35]
	v_mfma_f32_16x16x32_bf16 v[20:23], v[172:175], v[204:207], v[20:23]
	v_mfma_f32_16x16x32_bf16 v[16:19], v[180:183], v[204:207], v[16:19]
	v_mfma_f32_16x16x32_bf16 v[4:7], v[172:175], v[212:215], v[4:7]
	v_mfma_f32_16x16x32_bf16 v[0:3], v[180:183], v[212:215], v[0:3]
	s_setprio 0
	s_barrier
	s_add_i32 s53, s53, 2
	s_add_u32 s28, s28, 0x100
	s_addc_u32 s29, s29, 0
	s_add_u32 s51, s51, 0x100
	s_addc_u32 s52, s52, 0
	s_cmp_gt_u32 s53, 29
	s_cbranch_scc0 .LBB0_1562
	s_and_b64 vcc, exec, s[16:17]
	s_cbranch_vccz .LBB0_1565
	s_barrier

; __global__ void __launch_bounds__(512, 2) fwd(Params P) {
	.amdhsa_kernel _Z3fwd6Params
		.amdhsa_group_segment_fixed_size 0
		.amdhsa_private_segment_fixed_size 0
		.amdhsa_kernarg_size 432
		.amdhsa_user_sgpr_count 2
		.amdhsa_user_sgpr_dispatch_ptr 0
		.amdhsa_user_sgpr_queue_ptr 0
		.amdhsa_user_sgpr_kernarg_segment_ptr 1
		.amdhsa_user_sgpr_dispatch_id 0
		.amdhsa_user_sgpr_kernarg_preload_length 0
		.amdhsa_user_sgpr_kernarg_preload_offset 0
		.amdhsa_user_sgpr_private_segment_size 0
		.amdhsa_uses_dynamic_stack 0
		.amdhsa_enable_private_segment 0
		.amdhsa_system_sgpr_workgroup_id_x 1
		.amdhsa_system_sgpr_workgroup_id_y 0
		.amdhsa_system_sgpr_workgroup_id_z 0
		.amdhsa_system_sgpr_workgroup_info 0
		.amdhsa_system_vgpr_workitem_id 2
		.amdhsa_next_free_vgpr 248
		.amdhsa_next_free_sgpr 98
		.amdhsa_accum_offset 248
		.amdhsa_reserve_vcc 1
		.amdhsa_float_round_mode_32 0
		.amdhsa_float_round_mode_16_64 0
		.amdhsa_float_denorm_mode_32 3
		.amdhsa_float_denorm_mode_16_64 3
		.amdhsa_dx10_clamp 1
		.amdhsa_ieee_mode 1
		.amdhsa_fp16_overflow 0
		.amdhsa_tg_split 0
		.amdhsa_exception_fp_ieee_invalid_op 0
		.amdhsa_exception_fp_denorm_src 0
		.amdhsa_exception_fp_ieee_div_zero 0
		.amdhsa_exception_fp_ieee_overflow 0
		.amdhsa_exception_fp_ieee_underflow 0
		.amdhsa_exception_fp_ieee_inexact 0
		.amdhsa_exception_int_div_zero 0
	.end_amdhsa_kernel

; __global__ void __launch_bounds__(512, 2) fwd(Params P) {
amdhsa.kernels:
  - .agpr_count:     0
    .args:
      - .offset:         0
        .size:           176
        .value_kind:     by_value
      - .offset:         176
        .size:           4
        .value_kind:     hidden_block_count_x
      - .offset:         180
        .size:           4
        .value_kind:     hidden_block_count_y
      - .offset:         184
        .size:           4
        .value_kind:     hidden_block_count_z
      - .offset:         188
        .size:           2
        .value_kind:     hidden_group_size_x
      - .offset:         190
        .size:           2
        .value_kind:     hidden_group_size_y
      - .offset:         192
        .size:           2
        .value_kind:     hidden_group_size_z
      - .offset:         194
        .size:           2
        .value_kind:     hidden_remainder_x
      - .offset:         196
        .size:           2
        .value_kind:     hidden_remainder_y
      - .offset:         198
        .size:           2
        .value_kind:     hidden_remainder_z
      - .offset:         216
        .size:           8
        .value_kind:     hidden_global_offset_x
      - .offset:         224
        .size:           8
        .value_kind:     hidden_global_offset_y
      - .offset:         232
        .size:           8
        .value_kind:     hidden_global_offset_z
      - .offset:         240
        .size:           2
        .value_kind:     hidden_grid_dims
      - .offset:         264
        .size:           8
        .value_kind:     hidden_multigrid_sync_arg
      - .offset:         296
        .size:           4
        .value_kind:     hidden_dynamic_lds_size
    .group_segment_fixed_size: 0
    .kernarg_segment_align: 8
    .kernarg_segment_size: 432
    .language:       OpenCL C
    .language_version:
      - 2
      - 0
    .max_flat_workgroup_size: 512
    .name:           _Z3fwd6Params
    .private_segment_fixed_size: 0
    .sgpr_count:     104
    .sgpr_spill_count: 11
    .symbol:         _Z3fwd6Params.kd
    .uniform_work_group_size: 1
    .uses_dynamic_stack: false
    .vgpr_count:     248
    .vgpr_spill_count: 0
    .wavefront_size: 64
